# stack7 plus LayerNorm row loop: each row's four loads issued one row ahead of its reductions and stores
# speedup vs baseline: 1.0058x; 1.0058x over previous
; __device__ __forceinline__ void ln_rows(const Ctx& C, float* y, bf16_t* xb, const float* g, const float* b, f32x2* stats, const bool write_f32) {
;     f32x4 gg[4], bb[4];
; #pragma unroll
;     for (int j = 0; j < 4; ++j) { gg[j] = ((const f32x4*)g)[C.lane + 64 * j]; bb[j] = ((const f32x4*)b)[C.lane + 64 * j]; }
;     for (int m = C.gw; m < T; m += C.NGW) {
;         f32x4* row = (f32x4*)(y + (size_t)m * D) + C.lane; f32x4 v[4]; float s = 0.f;
; #pragma unroll
;         for (int j = 0; j < 4; ++j) { v[j] = row[64 * j]; s += (v[j].x + v[j].y) + (v[j].z + v[j].w); }
; __global__ void __launch_bounds__(512, 2) mk_fwd(Args a) {
;     ...
;                 const int li = (s == 2) ? 0 : (s == 7) ? 1 : 2;
;                 ln_rows(C, a.out, XB, a.in[14] + (l * 3 + li) * D, a.in[15] + (l * 3 + li) * D, (f32x2*)(ws + WS_STATS), l == DEPTH - 1 && s == 10);
.LBB0_381:
	s_andn2_b64 vcc, exec, s[0:1]
	s_cbranch_vccnz .LBB0_431
	s_cmp_eq_u32 s67, 2
	s_cselect_b64 s[18:19], -1, 0
	s_cmp_lg_u32 s67, 2
	s_cselect_b64 s[40:41], -1, 0
	s_cmp_eq_u32 s67, 7
	s_cselect_b64 s[28:29], -1, 0
	s_cmp_lg_u32 s67, 7
	s_cselect_b64 s[24:25], -1, 0
	s_cmpk_gt_i32 s38, 0x7fff
	s_cbranch_scc1 .LBB0_395
	s_cmp_eq_u32 s67, 10
	s_cselect_b64 s[42:43], -1, 0
	s_and_b64 s[28:29], s[28:29], exec
	s_cselect_b32 s12, 1, 2
	s_and_b64 s[18:19], s[18:19], exec
	s_cselect_b32 s12, 0, s12
	s_mul_i32 s13, s82, 3
	s_add_i32 s12, s12, s13
	s_lshl_b32 s18, s12, 10
	s_ashr_i32 s19, s18, 31
	v_readlane_b32 s44, v248, 28
	s_lshl_b64 s[18:19], s[18:19], 2
	v_readlane_b32 s56, v248, 40
	v_readlane_b32 s57, v248, 41
	s_add_u32 s28, s56, s18
	v_readlane_b32 s58, v248, 42
	s_addc_u32 s29, s57, s19
	v_readlane_b32 s59, v248, 43
	s_add_u32 s18, s58, s18
	v_lshlrev_b32_e32 v192, 4, v230
	s_addc_u32 s19, s59, s19
	s_waitcnt lgkmcnt(0)
	global_load_dwordx4 v[0:3], v192, s[28:29]
	global_load_dwordx4 v[4:7], v192, s[28:29] offset:1024
	global_load_dwordx4 v[8:11], v192, s[18:19]
	global_load_dwordx4 v[12:15], v192, s[18:19] offset:1024
	global_load_dwordx4 v[16:19], v192, s[28:29] offset:2048
	global_load_dwordx4 v[20:23], v192, s[28:29] offset:3072
	global_load_dwordx4 v[24:27], v192, s[18:19] offset:2048
	global_load_dwordx4 v[28:31], v192, s[18:19] offset:3072
	v_and_b32_e32 v32, 64, v226
	v_add_u32_e32 v32, 64, v32
	v_xor_b32_e32 v33, 1, v226
	v_cmp_lt_i32_e32 vcc, v33, v32
	s_sub_i32 s12, s3, 34
	s_cmp_lt_u32 s12, 11
	v_cndmask_b32_e32 v33, v226, v33, vcc
	v_lshlrev_b32_e32 v60, 2, v33
	v_xor_b32_e32 v33, 2, v226
	v_cmp_lt_i32_e32 vcc, v33, v32
	v_readlane_b32 s46, v248, 30
	v_readlane_b32 s47, v248, 31
	v_cndmask_b32_e32 v33, v226, v33, vcc
	v_lshlrev_b32_e32 v61, 2, v33
	v_xor_b32_e32 v33, 4, v226
	v_cmp_lt_i32_e32 vcc, v33, v32
	s_cselect_b64 s[18:19], -1, 0
	s_ashr_i32 s39, s38, 31
	v_cndmask_b32_e32 v33, v226, v33, vcc
	v_lshlrev_b32_e32 v62, 2, v33
	v_xor_b32_e32 v33, 8, v226
	v_cmp_lt_i32_e32 vcc, v33, v32
	s_and_b64 s[46:47], s[18:19], s[42:43]
	s_lshl_b64 s[18:19], s[38:39], 3
	v_cndmask_b32_e32 v33, v226, v33, vcc
	v_lshlrev_b32_e32 v63, 2, v33
	v_xor_b32_e32 v33, 16, v226
	v_cmp_lt_i32_e32 vcc, v33, v32
	s_add_u32 s20, s18, 0x10000
	s_addc_u32 s28, s19, 0
	v_cndmask_b32_e32 v33, v226, v33, vcc
	s_lshl_b64 s[18:19], s[38:39], 11
	v_lshlrev_b32_e32 v64, 2, v33
	v_xor_b32_e32 v33, 32, v226
	v_lshl_or_b32 v48, v230, 3, s18
	v_mov_b32_e32 v49, s19
	s_lshl_b64 s[18:19], s[38:39], 12
	v_readlane_b32 s0, v249, 62
	v_cmp_lt_i32_e32 vcc, v33, v32
	s_add_u32 s18, s0, s18
	v_readlane_b32 s0, v249, 63
	v_cndmask_b32_e32 v32, v226, v33, vcc
	s_addc_u32 s19, s0, s19
	v_lshlrev_b32_e32 v65, 2, v32
	v_cmp_eq_u32_e64 s[42:43], 0, v230
	v_lshl_add_u64 v[50:51], s[18:19], 0, v[192:193]
	s_mov_b32 s29, s38
	v_readlane_b32 s45, v248, 29
	v_readlane_b32 s48, v248, 32
	v_readlane_b32 s49, v248, 33
	v_readlane_b32 s50, v248, 34
	v_readlane_b32 s51, v248, 35
	v_readlane_b32 s52, v248, 36
	v_readlane_b32 s53, v248, 37
	v_readlane_b32 s54, v248, 38
	v_readlane_b32 s55, v248, 39
	global_load_dwordx4 v[66:69], v[50:51], off offset:-3072
	global_load_dwordx4 v[70:73], v[50:51], off offset:-2048
	global_load_dwordx4 v[74:77], v[50:51], off offset:-1024
	global_load_dwordx4 v[78:81], v[50:51], off
	s_waitcnt vmcnt(0)
	s_branch .LBB0_385

; __device__ __forceinline__ void ln_rows(const Ctx& C, float* y, bf16_t* xb, const float* g, const float* b, f32x2* stats, const bool write_f32) {
;     ...
;     for (int m = C.gw; m < T; m += C.NGW) {
;         f32x4* row = (f32x4*)(y + (size_t)m * D) + C.lane; f32x4 v[4]; float s = 0.f;
; #pragma unroll
;         for (int j = 0; j < 4; ++j) { v[j] = row[64 * j]; s += (v[j].x + v[j].y) + (v[j].z + v[j].w); }
;         const float mean = wave_sum(s) * (1.f / D); float s2 = 0.f;
; #pragma unroll
;         for (int j = 0; j < 4; ++j) { v[j] = v[j] - mean; s2 += (v[j].x * v[j].x + v[j].y * v[j].y) + (v[j].z * v[j].z + v[j].w * v[j].w); }
;         const float rstd = 1.f / sqrtf(wave_sum(s2) * (1.f / D) + LN_EPS);
;         if (C.lane == 0) stats[m] = (f32x2){mean, rstd};
.LBB0_385:
	s_waitcnt vmcnt(5)
	v_mov_b32_e32 v44, v66
	v_mov_b32_e32 v45, v67
	v_mov_b32_e32 v46, v68
	v_mov_b32_e32 v47, v69
	v_mov_b32_e32 v40, v70
	v_mov_b32_e32 v41, v71
	v_mov_b32_e32 v42, v72
	v_mov_b32_e32 v43, v73
	v_mov_b32_e32 v36, v74
	v_mov_b32_e32 v37, v75
	v_mov_b32_e32 v38, v76
	v_mov_b32_e32 v39, v77
	s_add_i32 s98, s29, s60
	s_cmp_lt_i32 s98, 0x8000
	s_cselect_b32 s99, 1, 0
	s_cbranch_scc0 .Lln_np1
	v_lshl_add_u64 v[82:83], v[50:51], 0, s[96:97]
	global_load_dwordx4 v[66:69], v[82:83], off offset:-3072
	global_load_dwordx4 v[70:73], v[82:83], off offset:-2048
	global_load_dwordx4 v[74:77], v[82:83], off offset:-1024
.Lln_np1:
	v_mov_b32_e32 v32, v45
	v_mov_b32_e32 v33, v46
	v_mov_b32_e32 v34, v44
	v_mov_b32_e32 v35, v47
	v_pk_add_f32 v[32:33], v[32:33], v[34:35]
	v_mov_b32_e32 v34, v40
	v_add_f32_e32 v32, v32, v33
	v_add_f32_e32 v52, 0, v32
	v_mov_b32_e32 v32, v41
	v_mov_b32_e32 v33, v42
	v_mov_b32_e32 v35, v43
	v_pk_add_f32 v[32:33], v[32:33], v[34:35]
	s_nop 0
	v_pk_add_f32 v[54:55], v[32:33], v[32:33] op_sel:[0,1] op_sel_hi:[1,0]
	v_mov_b32_e32 v32, v78
	v_mov_b32_e32 v33, v79
	v_mov_b32_e32 v34, v80
	v_mov_b32_e32 v35, v81
	s_cmp_eq_u32 s99, 1
	s_cbranch_scc0 .Lln_np2
	global_load_dwordx4 v[78:81], v[82:83], off
.Lln_np2:
	v_add_f32_e32 v56, v36, v37
	v_add_f32_e32 v58, v38, v39
	v_mov_b32_e32 v53, v32
	v_mov_b32_e32 v55, v33
	v_mov_b32_e32 v57, v34
	v_mov_b32_e32 v59, v35
	v_pk_add_f32 v[52:53], v[52:53], v[54:55]
	v_pk_add_f32 v[54:55], v[56:57], v[58:59]
	s_nop 0
	v_pk_add_f32 v[52:53], v[52:53], v[54:55]
	s_nop 0
	v_add_f32_e32 v52, v52, v53
	ds_bpermute_b32 v53, v60, v52
	s_waitcnt lgkmcnt(0)
	v_add_f32_e32 v52, v52, v53
	ds_bpermute_b32 v53, v61, v52
	s_waitcnt lgkmcnt(0)
	v_add_f32_e32 v52, v52, v53
	ds_bpermute_b32 v53, v62, v52
	s_waitcnt lgkmcnt(0)
	v_add_f32_e32 v52, v52, v53
	ds_bpermute_b32 v53, v63, v52
	s_waitcnt lgkmcnt(0)
	v_add_f32_e32 v52, v52, v53
	ds_bpermute_b32 v53, v64, v52
	s_waitcnt lgkmcnt(0)
	v_add_f32_e32 v52, v52, v53
	ds_bpermute_b32 v53, v65, v52
	s_waitcnt lgkmcnt(0)
	v_add_f32_e32 v59, v52, v53
	v_fmamk_f32 v57, v59, 0xba800000, v47
	v_fmamk_f32 v45, v59, 0xba800000, v45
	v_fmamk_f32 v55, v59, 0xba800000, v43
	v_fmamk_f32 v41, v59, 0xba800000, v41
	v_fmamk_f32 v56, v59, 0xba800000, v46
	v_fmac_f32_e32 v44, 0xba800000, v59
	v_mul_f32_e32 v46, v45, v45
	v_mul_f32_e32 v47, v57, v57
	v_fmamk_f32 v54, v59, 0xba800000, v42
	v_fmac_f32_e32 v40, 0xba800000, v59
	v_mul_f32_e32 v42, v41, v41
	v_mul_f32_e32 v43, v55, v55
	v_fmac_f32_e32 v46, v44, v44
	v_fmac_f32_e32 v47, v56, v56
	v_fmac_f32_e32 v42, v40, v40
	v_fmac_f32_e32 v43, v54, v54
	v_fmamk_f32 v53, v59, 0xba800000, v39
	v_fmamk_f32 v37, v59, 0xba800000, v37
	v_add_f32_e32 v46, v46, v47
	v_add_f32_e32 v42, v42, v43
	v_fmamk_f32 v52, v59, 0xba800000, v38
	v_fmac_f32_e32 v36, 0xba800000, v59
	v_mul_f32_e32 v38, v37, v37
	v_mul_f32_e32 v39, v53, v53
	v_fmamk_f32 v47, v59, 0xba800000, v35
	v_fmamk_f32 v33, v59, 0xba800000, v33
	v_add_f32_e32 v42, v46, v42
	v_fmac_f32_e32 v38, v36, v36
	v_fmac_f32_e32 v39, v52, v52
	v_fmamk_f32 v46, v59, 0xba800000, v34
	v_fmac_f32_e32 v32, 0xba800000, v59
	v_mul_f32_e32 v34, v33, v33
	v_mul_f32_e32 v35, v47, v47
	v_add_f32_e32 v38, v38, v39
	v_fmac_f32_e32 v34, v32, v32
	v_fmac_f32_e32 v35, v46, v46
	v_add_f32_e32 v38, v38, v42
	v_add_f32_e32 v34, v34, v35
	v_add_f32_e32 v34, v34, v38
	ds_bpermute_b32 v35, v60, v34
	s_waitcnt lgkmcnt(0)
	v_add_f32_e32 v34, v34, v35
	ds_bpermute_b32 v35, v61, v34
	s_waitcnt lgkmcnt(0)
	v_add_f32_e32 v34, v34, v35
	ds_bpermute_b32 v35, v62, v34
	s_waitcnt lgkmcnt(0)
	v_add_f32_e32 v34, v34, v35
	ds_bpermute_b32 v35, v63, v34
	s_waitcnt lgkmcnt(0)
	v_add_f32_e32 v34, v34, v35
	ds_bpermute_b32 v35, v64, v34
	s_waitcnt lgkmcnt(0)
	v_add_f32_e32 v34, v34, v35
	ds_bpermute_b32 v35, v65, v34
	s_waitcnt lgkmcnt(0)
	v_add_f32_e32 v34, v34, v35
	v_fmamk_f32 v34, v34, 0x3a800000, v223
	v_cmp_gt_f32_e32 vcc, s10, v34
	v_mul_f32_e32 v35, 0x4f800000, v34
	s_nop 0
	v_cndmask_b32_e32 v34, v34, v35, vcc
	v_sqrt_f32_e32 v35, v34
	s_nop 0
	v_add_u32_e32 v38, -1, v35
	v_fma_f32 v39, -v38, v35, v34
	v_cmp_ge_f32_e64 s[44:45], 0, v39
	v_add_u32_e32 v39, 1, v35
	s_nop 0
	v_cndmask_b32_e64 v38, v35, v38, s[44:45]
	v_fma_f32 v35, -v39, v35, v34
	v_cmp_lt_f32_e64 s[44:45], 0, v35
	s_nop 1
	v_cndmask_b32_e64 v35, v38, v39, s[44:45]
	v_mul_f32_e32 v38, 0x37800000, v35
	v_cndmask_b32_e32 v35, v35, v38, vcc
	v_cmp_class_f32_e32 vcc, v34, v224
	s_nop 1
	v_cndmask_b32_e32 v34, v35, v34, vcc
	v_div_scale_f32 v35, s[18:19], v34, v34, 1.0
	v_rcp_f32_e32 v38, v35
	s_nop 0
	v_fma_f32 v39, -v35, v38, 1.0
	v_fmac_f32_e32 v38, v39, v38
	v_div_scale_f32 v39, vcc, 1.0, v34, 1.0
	v_mul_f32_e32 v42, v39, v38
	v_fma_f32 v43, -v35, v42, v39
	v_fmac_f32_e32 v42, v43, v38
	v_fma_f32 v35, -v35, v42, v39
	v_div_fmas_f32 v35, v35, v38, v42
	v_div_fixup_f32 v58, v35, v34, 1.0
	s_and_saveexec_b64 s[18:19], s[42:43]
	s_cbranch_execz .LBB0_387
	s_add_u32 s44, s62, s20
	v_mul_f32_e32 v34, 0x3a800000, v59
	s_addc_u32 s45, s63, s28
	v_mov_b32_e32 v35, v58
	global_store_dwordx2 v193, v[34:35], s[44:45]
